# adds attention mainloop: one static s_setprio 1 for waves 4-7 over the steady-state loop
# baseline (speedup 1.0000x reference)
; #define SLOAD(i, k0) do { sr_[i].vs0 = St::ld8(&Vh[(long)((k0) + sr) * LDK + sc]); sr_[i].vs1 = St::ld8(&Vh[(long)((k0) + 32 + sr) * LDK + sc]); \
;     sr_[i].ks0 = St::ld8(&Kh[(long)((k0) + sr) * LDK + sc]); sr_[i].ks1 = St::ld8(&Kh[(long)((k0) + 32 + sr) * LDK + sc]); } while (0)
; #define SWRITE(bo, i) do { *(bf16x8*)((char*)V_lds + (bo) + vst0) = St::tobf(sr_[i].vs0);            \
;     *(bf16x8*)((char*)V_lds + (bo) + vst1) = St::tobf(sr_[i].vs1); int kc = sc * 2;               \
;     *(bf16x8*)((char*)K_lds + (bo) + KSWZ(sr, kc)) = St::tobf(sr_[i].ks0);                       \
;     *(bf16x8*)((char*)K_lds + (bo) + KSWZ(32 + sr, kc)) = St::tobf(sr_[i].ks1); } while (0)
; #define SWAIT() do { if constexpr (SDEPTH == 2) asm volatile("s_waitcnt vmcnt(4)" ::: "memory"); else asm volatile("s_waitcnt vmcnt(0)" ::: "memory"); } while (0)
; template <typename TQ> ...
;     ...
;   f32x16 pA0, pA1, pB0, pB1; float mnA, mnB, alA, alB; bf16x8 pa0, pa1, pa2, pa3; const int NT = seq / KVBLK;
;   static_assert(SHM_V == SHM_K, "one buffer offset serves K and V");
;   constexpr int SE = 0, SO = SDEPTH - 1;
;   SLOAD(SE, 0); asm volatile("s_waitcnt vmcnt(0)" ::: "memory"); SWRITE(0, SE); __syncthreads();
;   qkt(pA0, pA1, K_lds, qr, r32, hi); partialSM(pA0, pA1, m_reg, mnA, alA, bounded);
;   SLOAD(SO, KVBLK); if constexpr (SDEPTH == 2) { if (2 < NT) SLOAD(SE, 2 * KVBLK); }
;   SWAIT(); SWRITE((int)SHM_K, SO); __syncthreads();
;   int o_prev = 0, o_cur = (int)SHM_K, o_nxt = 2 * (int)SHM_K;
.LBB0_893:
	v_lshl_or_b32 v28, v26, 1, v16
	v_mov_b32_e32 v29, v17
	s_mov_b64 s[10:11], 0x4000
	v_lshl_add_u64 v[32:33], v[28:29], 0, s[10:11]
	s_mov_b64 s[10:11], 0x6000
	v_lshl_add_u64 v[34:35], v[28:29], 0, s[10:11]
	v_lshl_add_u64 v[18:19], s[38:39], 0, v[32:33]
	v_lshl_add_u64 v[22:23], s[38:39], 0, v[34:35]
	v_lshl_add_u64 v[32:33], s[34:35], 0, v[32:33]
	v_lshl_add_u64 v[36:37], s[34:35], 0, v[34:35]
	global_load_dwordx4 v[18:21], v[18:19], off
	s_nop 0
	global_load_dwordx4 v[22:25], v[22:23], off
	s_nop 0
	global_load_dwordx4 v[32:35], v[32:33], off
	s_nop 0
	global_load_dwordx4 v[36:39], v[36:37], off
	v_lshl_add_u64 v[40:41], v[28:29], 0, s[74:75]
	s_mov_b64 s[10:11], 0xa000
	v_lshl_add_u64 v[42:43], s[38:39], 0, v[40:41]
	v_lshl_add_u64 v[28:29], v[28:29], 0, s[10:11]
	v_lshl_add_u64 v[40:41], s[34:35], 0, v[40:41]
	v_lshl_add_u64 v[44:45], s[38:39], 0, v[28:29]
	global_load_dwordx4 v[144:147], v[42:43], off
	global_load_dwordx4 v[152:155], v[44:45], off
	v_lshl_add_u64 v[28:29], s[34:35], 0, v[28:29]
	global_load_dwordx4 v[148:151], v[40:41], off
	global_load_dwordx4 v[156:159], v[28:29], off
	s_add_i32 s10, 0, 0x18000
	v_lshlrev_b32_e32 v29, 4, v199
	v_lshlrev_b32_e32 v28, 3, v199
	v_lshlrev_b32_e32 v31, 1, v199
	v_exp_f32_e32 v161, v12
	v_exp_f32_e32 v163, v13
	v_exp_f32_e32 v160, v14
	v_exp_f32_e32 v162, v15
	v_mad_i64_i32 v[12:13], s[4:5], s4, v195, v[16:17]
	v_and_b32_e32 v14, 15, v179
	v_and_b32_e32 v15, 0xc0, v29
	s_cmp_lg_u32 0, -1
	v_exp_f32_e32 v173, v0
	v_exp_f32_e32 v175, v1
	v_exp_f32_e32 v171, v2
	v_exp_f32_e32 v174, v3
	v_exp_f32_e32 v170, v4
	v_exp_f32_e32 v172, v5
	v_exp_f32_e32 v168, v6
	v_exp_f32_e32 v169, v7
	v_exp_f32_e32 v165, v8
	v_exp_f32_e32 v167, v9
	v_exp_f32_e32 v164, v10
	v_exp_f32_e32 v166, v11
	v_and_b32_e32 v16, 32, v31
	v_and_b32_e32 v17, 0x100, v28
	v_lshl_or_b32 v12, v14, 4, v12
	v_and_or_b32 v14, v28, 24, v15
	s_cselect_b32 s4, 0, 0
	s_add_i32 s5, 0, 0x10000
	v_and_b32_e32 v26, 0x3fffffc0, v179
	v_lshl_add_u64 v[182:183], s[72:73], 0, v[12:13]
	v_or3_b32 v216, v14, v16, v17
	s_waitcnt vmcnt(4)
	v_add_u32_e32 v12, s5, v208
	v_add_u32_e32 v13, s5, v210
	v_mov_b32_e32 v14, v177
	v_mov_b32_e32 v15, v177
	v_mov_b32_e32 v0, v177
	v_mov_b32_e32 v1, v177
	v_mov_b32_e32 v2, v177
	v_mov_b32_e32 v3, v177
	v_mov_b32_e32 v4, v177
	v_mov_b32_e32 v5, v177
	v_mov_b32_e32 v6, v177
	v_mov_b32_e32 v7, v177
	v_mov_b32_e32 v8, v177
	v_mov_b32_e32 v9, v177
	v_mov_b32_e32 v10, v177
	v_mov_b32_e32 v11, v177
	v_lshl_add_u32 v179, v26, 2, s10
	s_mov_b32 s3, 1
	s_mov_b32 s9, 0
	v_cmp_gt_u32_e64 s[40:41], 32, v199
	v_lshl_add_u32 v181, v197, 2, v179
	v_add_u32_e32 v217, s4, v216
	v_mov_b32_e32 v200, 0
	s_movk_i32 s10, 0x4000
	s_mov_b32 s4, 0x8000
	s_waitcnt vmcnt(7)
	ds_write_b128 v27, v[18:21] offset:16384
	s_waitcnt vmcnt(6)
	ds_write_b128 v30, v[22:25] offset:16384
	s_waitcnt vmcnt(5)
	ds_write_b128 v12, v[32:35]
	s_waitcnt vmcnt(4)
	ds_write_b128 v13, v[36:39]
	v_mov_b32_e32 v12, v177
	v_mov_b32_e32 v13, v177
	v_mov_b64_e32 v[62:63], v[14:15]
	v_mov_b64_e32 v[46:47], v[14:15]
	v_mov_b64_e32 v[30:31], v[14:15]
	v_mov_b64_e32 v[60:61], v[12:13]
	v_mov_b64_e32 v[58:59], v[10:11]
	v_mov_b64_e32 v[56:57], v[8:9]
	v_mov_b64_e32 v[54:55], v[6:7]
	v_mov_b64_e32 v[52:53], v[4:5]
	v_mov_b64_e32 v[50:51], v[2:3]
	v_mov_b64_e32 v[48:49], v[0:1]
	v_mov_b64_e32 v[44:45], v[12:13]
	v_mov_b64_e32 v[42:43], v[10:11]
	v_mov_b64_e32 v[40:41], v[8:9]
	v_mov_b64_e32 v[38:39], v[6:7]
	v_mov_b64_e32 v[36:37], v[4:5]
	v_mov_b64_e32 v[34:35], v[2:3]
	v_mov_b64_e32 v[32:33], v[0:1]
	v_mov_b64_e32 v[28:29], v[12:13]
	v_mov_b64_e32 v[26:27], v[10:11]
	v_mov_b64_e32 v[24:25], v[8:9]
	v_mov_b64_e32 v[22:23], v[6:7]
	v_mov_b64_e32 v[20:21], v[4:5]
	v_mov_b64_e32 v[18:19], v[2:3]
	v_mov_b64_e32 v[16:17], v[0:1]
	s_cmp_lt_u32 s98, 4
	s_cbranch_scc1 .Lmy_attn_p0
	s_setprio 1

; #define SBAR() __builtin_amdgcn_sched_barrier(0)
; __device__ __forceinline__ void finishSM(f32x16& p0, f32x16& p1, float alpha, float& l_reg, bf16x8& pa0, bf16x8& pa1, bf16x8& pa2, bf16x8& pa3) {
;   for (int r = 0; r < 16; ++r) p1[r] = __builtin_amdgcn_exp2f(p1[r]);
;   float ps = 0; for (int r = 0; r < 16; ++r) ps += p0[r]; for (int r = 0; r < 16; ++r) ps += p1[r];
;   { auto rr = __builtin_amdgcn_permlane32_swap(__float_as_uint(ps), __float_as_uint(ps), false, false);
;     ps = __uint_as_float(rr[0]) + __uint_as_float(rr[1]); }
;   l_reg = l_reg * alpha + ps;
;     ...
;   PK4(p0, 0, pa0); PK4(p0, 8, pa1); PK4(p1, 0, pa2); PK4(p1, 8, pa3);
;     ...
; }
; __device__ __forceinline__ void qkt(f32x16& p0, f32x16& p1, const bf16* Ks, const bf16x8* qr, int r32, int hi) {
;   p0 = f32x16{}; p1 = f32x16{};
;   for (int d0 = 0; d0 < 8; ++d0) { int cb = (d0 * 16 + hi * 8) * 2;
;     bf16x8 b0 = *reinterpret_cast<const bf16x8*>((const char*)Ks + KSWZ(r32, cb));
;     bf16x8 b1 = *reinterpret_cast<const bf16x8*>((const char*)Ks + KSWZ(32 + r32, cb));
;     p0 = __builtin_amdgcn_mfma_f32_32x32x16_bf16(b0, qr[d0], p0, 0, 0, 0);
;     p1 = __builtin_amdgcn_mfma_f32_32x32x16_bf16(b1, qr[d0], p1, 0, 0, 0); }
; }
; template <typename TQ> ...
;     ...
;   SBAR(); qkt(pB0, pB1, (bf16*)((char*)K_lds + o_cur), qr, r32, hi);
;   finishSM(pA0, pA1, alA, l_reg, pa0, pa1, pa2, pa3); SBAR();
.LBB0_910:
	s_setprio 0
	v_add_u32_e32 v84, s12, v213
	ds_read_b128 v[80:83], v84 offset:49152
	ds_read_b128 v[84:87], v84 offset:57344
	v_add_u32_e32 v144, s12, v215
	v_exp_f32_e32 v78, v78
	v_exp_f32_e32 v79, v79
	s_waitcnt lgkmcnt(1)
	v_mfma_f32_32x32x16_bf16 v[96:111], v[80:83], v[136:139], 0
	s_waitcnt lgkmcnt(0)
	v_mfma_f32_32x32x16_bf16 v[80:95], v[84:87], v[136:139], 0
	ds_read_b128 v[136:139], v144 offset:49152
	ds_read_b128 v[144:147], v144 offset:57344
	s_waitcnt lgkmcnt(1)
	v_mfma_f32_32x32x16_bf16 v[96:111], v[136:139], v[140:143], v[96:111]
	s_waitcnt lgkmcnt(0)
	v_mfma_f32_32x32x16_bf16 v[80:95], v[144:147], v[140:143], v[80:95]
	v_add_u32_e32 v140, s12, v214
	ds_read_b128 v[136:139], v140 offset:49152
	ds_read_b128 v[140:143], v140 offset:57344
	s_waitcnt lgkmcnt(1)
	v_mfma_f32_32x32x16_bf16 v[96:111], v[136:139], v[128:131], v[96:111]
	v_add_u32_e32 v136, s12, v211
	s_waitcnt lgkmcnt(0)
	v_mfma_f32_32x32x16_bf16 v[80:95], v[140:143], v[128:131], v[80:95]
	ds_read_b128 v[128:131], v136 offset:49152
	ds_read_b128 v[136:139], v136 offset:57344
	s_waitcnt lgkmcnt(1)
	v_mfma_f32_32x32x16_bf16 v[96:111], v[128:131], v[132:135], v[96:111]
	s_waitcnt lgkmcnt(0)
	v_mfma_f32_32x32x16_bf16 v[80:95], v[136:139], v[132:135], v[80:95]
	v_add_u32_e32 v132, s12, v209
	ds_read_b128 v[128:131], v132 offset:49152
	ds_read_b128 v[132:135], v132 offset:57344
	s_waitcnt lgkmcnt(1)
	v_mfma_f32_32x32x16_bf16 v[96:111], v[128:131], v[124:127], v[96:111]
	v_add_u32_e32 v128, s12, v206
	s_waitcnt lgkmcnt(0)
	v_mfma_f32_32x32x16_bf16 v[80:95], v[132:135], v[124:127], v[80:95]
	ds_read_b128 v[124:127], v128 offset:49152
	ds_read_b128 v[128:131], v128 offset:57344
	s_waitcnt lgkmcnt(1)
	v_mfma_f32_32x32x16_bf16 v[96:111], v[124:127], v[116:119], v[96:111]
	v_add_u32_e32 v124, s12, v207
	s_waitcnt lgkmcnt(0)
	v_mfma_f32_32x32x16_bf16 v[80:95], v[128:131], v[116:119], v[80:95]
	ds_read_b128 v[116:119], v124 offset:49152
	ds_read_b128 v[124:127], v124 offset:57344
	s_waitcnt lgkmcnt(1)
	v_mfma_f32_32x32x16_bf16 v[96:111], v[116:119], v[120:123], v[96:111]
	s_waitcnt lgkmcnt(0)
	v_mfma_f32_32x32x16_bf16 v[80:95], v[124:127], v[120:123], v[80:95]
	v_add_u32_e32 v120, s12, v212
	ds_read_b128 v[116:119], v120 offset:49152
	ds_read_b128 v[120:123], v120 offset:57344
	v_exp_f32_e32 v124, v76
	v_exp_f32_e32 v125, v77
	s_waitcnt lgkmcnt(1)
	v_mfma_f32_32x32x16_bf16 v[96:111], v[116:119], v[112:115], v[96:111]
	v_exp_f32_e32 v116, v68
	v_exp_f32_e32 v117, v69
	v_exp_f32_e32 v118, v70
	v_exp_f32_e32 v119, v71
	s_waitcnt lgkmcnt(0)
	v_mfma_f32_32x32x16_bf16 v[80:95], v[120:123], v[112:115], v[80:95]
	v_exp_f32_e32 v112, v64
	v_add_f32_e32 v64, 0, v173
	v_add_f32_e32 v64, v175, v64
	v_add_f32_e32 v64, v171, v64
	v_add_f32_e32 v64, v174, v64
	v_add_f32_e32 v64, v170, v64
	v_add_f32_e32 v64, v172, v64
	v_add_f32_e32 v64, v168, v64
	v_add_f32_e32 v64, v169, v64
	v_add_f32_e32 v64, v165, v64
	v_add_f32_e32 v64, v167, v64
	v_add_f32_e32 v64, v164, v64
	v_add_f32_e32 v64, v166, v64
	v_add_f32_e32 v64, v161, v64
	v_exp_f32_e32 v113, v65
	v_add_f32_e32 v64, v163, v64
	v_exp_f32_e32 v114, v66
	v_add_f32_e32 v64, v160, v64
	v_exp_f32_e32 v115, v67
	v_add_f32_e32 v64, v162, v64
	v_add_f32_e32 v64, v112, v64
	v_add_f32_e32 v64, v113, v64
	v_add_f32_e32 v64, v114, v64
	v_add_f32_e32 v64, v115, v64
	v_exp_f32_e32 v120, v72
	v_add_f32_e32 v64, v116, v64
	v_exp_f32_e32 v121, v73
	v_add_f32_e32 v64, v117, v64
	v_exp_f32_e32 v122, v74
	v_add_f32_e32 v64, v118, v64
	v_exp_f32_e32 v123, v75
	v_add_f32_e32 v64, v119, v64
	v_add_f32_e32 v64, v120, v64
	v_add_f32_e32 v64, v121, v64
	v_add_f32_e32 v64, v122, v64
	v_add_f32_e32 v64, v123, v64
	v_add_f32_e32 v64, v124, v64
	v_add_f32_e32 v64, v125, v64
	v_add_f32_e32 v64, v78, v64
	v_add_f32_e32 v68, v79, v64
	v_mov_b32_e32 v69, v68
	v_cvt_pk_bf16_f32 v64, v173, v175
	v_cvt_pk_bf16_f32 v65, v171, v174
	v_cvt_pk_bf16_f32 v66, v170, v172
	s_nop 1
	v_permlane32_swap_b32_e32 v68, v69
	v_cvt_pk_bf16_f32 v67, v168, v169
	v_permlane32_swap_b32_e32 v64, v66
	v_cvt_pk_bf16_f32 v70, v165, v167
	v_cvt_pk_bf16_f32 v71, v164, v166
	v_cvt_pk_bf16_f32 v72, v161, v163
	v_cvt_pk_bf16_f32 v73, v160, v162
	v_cvt_pk_bf16_f32 v74, v112, v113
	v_cvt_pk_bf16_f32 v75, v114, v115
	v_cvt_pk_bf16_f32 v76, v116, v117
	v_cvt_pk_bf16_f32 v77, v118, v119
	v_cvt_pk_bf16_f32 v112, v120, v121
	v_cvt_pk_bf16_f32 v113, v122, v123
	v_cvt_pk_bf16_f32 v114, v124, v125
	v_cvt_pk_bf16_f32 v115, v78, v79
	v_permlane32_swap_b32_e32 v65, v67
	v_permlane32_swap_b32_e32 v70, v72
	v_permlane32_swap_b32_e32 v71, v73
	v_permlane32_swap_b32_e32 v74, v76
	v_permlane32_swap_b32_e32 v75, v77
	v_permlane32_swap_b32_e32 v112, v114
	v_permlane32_swap_b32_e32 v113, v115
	s_cmp_lg_u32 0, -1
	s_cselect_b32 s0, 0, 0
	s_addk_i32 s0, 0x4000
	v_add_u32_e32 v78, s0, v216
	ds_read_b64_tr_b16 v[116:117], v78 offset:0
	ds_read_b64_tr_b16 v[118:119], v78 offset:0x800
	ds_read_b64_tr_b16 v[120:121], v78 offset:0x1000
	ds_read_b64_tr_b16 v[122:123], v78 offset:0x1800
	ds_read_b64_tr_b16 v[124:125], v78 offset:0x2000
	ds_read_b64_tr_b16 v[126:127], v78 offset:0x2800
	ds_read_b64_tr_b16 v[128:129], v78 offset:0x3000
	ds_read_b64_tr_b16 v[130:131], v78 offset:0x3800
	s_waitcnt lgkmcnt(0)
; #define SBAR() __builtin_amdgcn_sched_barrier(0)
; __device__ __forceinline__ void partialSM(f32x16& p0, f32x16& p1, float& m_reg, float& mn, float& alpha, bool bounded) {
;   constexpr float THRL = THR * 1.4426950408889634f;
;   if (bounded) { mn = m_reg; alpha = 1.f; }
;   else {
;     float pmax = p0[0]; for (int r = 1; r < 16; ++r) pmax = fmaxf(pmax, p0[r]); for (int r = 0; r < 16; ++r) pmax = fmaxf(pmax, p1[r]);
;     { auto rr = __builtin_amdgcn_permlane32_swap(__float_as_uint(pmax), __float_as_uint(pmax), false, false);
;       pmax = fmaxf(__uint_as_float(rr[0]), __uint_as_float(rr[1])); }
;     if (__builtin_expect(__all(pmax - m_reg <= THRL), 1)) { mn = m_reg; alpha = 1.f; }
;     else { mn = fmaxf(m_reg, pmax); alpha = __builtin_amdgcn_exp2f(m_reg - mn); m_reg = mn; }
;     for (int r = 0; r < 16; ++r) p0[r] -= mn; for (int r = 0; r < 16; ++r) p1[r] -= mn;
;   }
;   for (int r = 0; r < 16; ++r) p0[r] = __builtin_amdgcn_exp2f(p0[r]);
; }
; template <int D0> __device__ __forceinline__ void pv_one(f32x16& od, int vb, bf16x8 pa0, bf16x8 pa1, bf16x8 pa2, bf16x8 pa3) {
;   const s16x4 l0 = tr_read<v_rd_off(D0, 0, 0)>(vb), h0 = tr_read<v_rd_off(D0, 0, 1)>(vb), l1 = tr_read<v_rd_off(D0, 1, 0)>(vb), h1 = tr_read<v_rd_off(D0, 1, 1)>(vb);
;   const s16x4 l2 = tr_read<v_rd_off(D0, 2, 0)>(vb), h2 = tr_read<v_rd_off(D0, 2, 1)>(vb), l3 = tr_read<v_rd_off(D0, 3, 0)>(vb), h3 = tr_read<v_rd_off(D0, 3, 1)>(vb);
;   asm volatile("s_waitcnt lgkmcnt(0)" ::: "memory"); SBAR();
;     ...
;   od = __builtin_amdgcn_mfma_f32_32x32x16_bf16(pa0, PK(l0, h0), od, 0, 0, 0);
;   od = __builtin_amdgcn_mfma_f32_32x32x16_bf16(pa1, PK(l1, h1), od, 0, 0, 0);
;   od = __builtin_amdgcn_mfma_f32_32x32x16_bf16(pa2, PK(l2, h2), od, 0, 0, 0);
;   od = __builtin_amdgcn_mfma_f32_32x32x16_bf16(pa3, PK(l3, h3), od, 0, 0, 0);
;     ...
; }
; __device__ __forceinline__ void pv_d0(f32x16* o, int vb, bf16x8 pa0, bf16x8 pa1, bf16x8 pa2, bf16x8 pa3) {
;   pv_one<0>(o[0], vb, pa0, pa1, pa2, pa3); pv_one<1>(o[1], vb, pa0, pa1, pa2, pa3); pv_one<2>(o[2], vb, pa0, pa1, pa2, pa3); pv_one<3>(o[3], vb, pa0, pa1, pa2, pa3);
	s_nop 0
	v_mfma_f32_32x32x16_bf16 v[0:15], v[64:67], v[116:119], v[0:15]
	ds_read_b64_tr_b16 v[116:117], v78 offset:0x200
	ds_read_b64_tr_b16 v[118:119], v78 offset:0xa00
	v_mfma_f32_32x32x16_bf16 v[0:15], v[70:73], v[120:123], v[0:15]
	ds_read_b64_tr_b16 v[120:121], v78 offset:0x1200
	ds_read_b64_tr_b16 v[122:123], v78 offset:0x1a00
	v_mfma_f32_32x32x16_bf16 v[0:15], v[74:77], v[124:127], v[0:15]
	ds_read_b64_tr_b16 v[124:125], v78 offset:0x2200
	ds_read_b64_tr_b16 v[126:127], v78 offset:0x2a00
	v_mfma_f32_32x32x16_bf16 v[0:15], v[112:115], v[128:131], v[0:15]
	ds_read_b64_tr_b16 v[128:129], v78 offset:0x3200
	ds_read_b64_tr_b16 v[130:131], v78 offset:0x3a00
	s_waitcnt lgkmcnt(0)
	v_mfma_f32_32x32x16_bf16 v[48:63], v[64:67], v[116:119], v[48:63]
	ds_read_b64_tr_b16 v[116:117], v78 offset:0x400
	ds_read_b64_tr_b16 v[118:119], v78 offset:0xc00
	v_mfma_f32_32x32x16_bf16 v[48:63], v[70:73], v[120:123], v[48:63]
	ds_read_b64_tr_b16 v[120:121], v78 offset:0x1400
	ds_read_b64_tr_b16 v[122:123], v78 offset:0x1c00
	v_mfma_f32_32x32x16_bf16 v[48:63], v[74:77], v[124:127], v[48:63]
	ds_read_b64_tr_b16 v[124:125], v78 offset:0x2400
	ds_read_b64_tr_b16 v[126:127], v78 offset:0x2c00
	v_mfma_f32_32x32x16_bf16 v[48:63], v[112:115], v[128:131], v[48:63]
	ds_read_b64_tr_b16 v[128:129], v78 offset:0x3400
	ds_read_b64_tr_b16 v[130:131], v78 offset:0x3c00
	s_waitcnt lgkmcnt(0)
	v_mfma_f32_32x32x16_bf16 v[32:47], v[64:67], v[116:119], v[32:47]
	ds_read_b64_tr_b16 v[116:117], v78 offset:0x600
	ds_read_b64_tr_b16 v[118:119], v78 offset:0xe00
	v_mfma_f32_32x32x16_bf16 v[32:47], v[70:73], v[120:123], v[32:47]
	ds_read_b64_tr_b16 v[120:121], v78 offset:0x1600
	ds_read_b64_tr_b16 v[122:123], v78 offset:0x1e00
	v_mfma_f32_32x32x16_bf16 v[32:47], v[74:77], v[124:127], v[32:47]
	ds_read_b64_tr_b16 v[124:125], v78 offset:0x2600
	ds_read_b64_tr_b16 v[126:127], v78 offset:0x2e00
	v_mfma_f32_32x32x16_bf16 v[32:47], v[112:115], v[128:131], v[32:47]
	ds_read_b64_tr_b16 v[128:129], v78 offset:0x3600
	ds_read_b64_tr_b16 v[130:131], v78 offset:0x3e00
	s_waitcnt lgkmcnt(0)
	v_mfma_f32_32x32x16_bf16 v[16:31], v[64:67], v[116:119], v[16:31]
	v_mov_b32_e32 v64, 1.0
	s_and_b64 vcc, exec, s[42:43]
	v_mfma_f32_32x32x16_bf16 v[16:31], v[70:73], v[120:123], v[16:31]
	v_mfma_f32_32x32x16_bf16 v[16:31], v[74:77], v[124:127], v[16:31]
	v_mfma_f32_32x32x16_bf16 v[16:31], v[112:115], v[128:131], v[16:31]
	s_cbranch_vccnz .LBB0_912
	v_max_f32_e32 v64, v97, v97
	v_max_f32_e32 v65, v96, v96
	v_max_f32_e32 v64, v65, v64
	v_max3_f32 v64, v64, v98, v99
	v_max3_f32 v64, v64, v100, v101
	v_max3_f32 v64, v64, v102, v103
	v_max3_f32 v64, v64, v104, v105
	v_max3_f32 v64, v64, v106, v107
	v_max3_f32 v64, v64, v108, v109
	v_max3_f32 v64, v64, v110, v111
	v_max3_f32 v64, v64, v80, v81
	v_max3_f32 v64, v64, v82, v83
	v_max3_f32 v64, v64, v84, v85
	v_max3_f32 v64, v64, v86, v87
	v_max3_f32 v64, v64, v88, v89
	v_max3_f32 v64, v64, v90, v91
	v_max3_f32 v64, v64, v92, v93
	v_max3_f32 v64, v64, v94, v95
	v_mov_b32_e32 v65, v64
	s_nop 1
	v_permlane32_swap_b32_e32 v64, v65
	v_max_f32_e32 v65, v65, v65
	v_max_f32_e32 v64, v64, v64
	v_max_f32_e32 v64, v64, v65
	v_sub_f32_e32 v65, v64, v201
	v_cmp_ge_f32_e32 vcc, s8, v65
	v_max_f32_e32 v65, v201, v201
	v_max_f32_e32 v64, v65, v64
	v_sub_f32_e32 v65, v201, v64
	v_exp_f32_e32 v65, v65
	s_cmp_eq_u64 vcc, exec
	s_cselect_b64 vcc, -1, 0
	v_cndmask_b32_e32 v66, v64, v201, vcc
	v_cndmask_b32_e64 v64, v65, 1.0, vcc
	v_sub_f32_e32 v111, v111, v66
	v_sub_f32_e32 v110, v110, v66
	v_sub_f32_e32 v109, v109, v66
	v_sub_f32_e32 v108, v108, v66
	v_sub_f32_e32 v107, v107, v66
	v_sub_f32_e32 v106, v106, v66
	v_sub_f32_e32 v105, v105, v66
	v_sub_f32_e32 v104, v104, v66
	v_sub_f32_e32 v103, v103, v66
	v_sub_f32_e32 v102, v102, v66
	v_sub_f32_e32 v101, v101, v66
	v_sub_f32_e32 v100, v100, v66
	v_sub_f32_e32 v99, v99, v66
	v_sub_f32_e32 v98, v98, v66
	v_sub_f32_e32 v97, v97, v66
	v_sub_f32_e32 v96, v96, v66
	v_sub_f32_e32 v95, v95, v66
	v_sub_f32_e32 v94, v94, v66
	v_sub_f32_e32 v93, v93, v66
	v_sub_f32_e32 v92, v92, v66
	v_sub_f32_e32 v91, v91, v66
	v_sub_f32_e32 v90, v90, v66
	v_sub_f32_e32 v89, v89, v66
	v_sub_f32_e32 v88, v88, v66
	v_sub_f32_e32 v87, v87, v66
	v_sub_f32_e32 v86, v86, v66
	v_sub_f32_e32 v85, v85, v66
	v_sub_f32_e32 v84, v84, v66
	v_sub_f32_e32 v83, v83, v66
	v_sub_f32_e32 v82, v82, v66
	v_sub_f32_e32 v81, v81, v66
	v_sub_f32_e32 v80, v80, v66
